# hand-written sample SSD recurrence: B/C/x staged once per item through LDS, next item prefetched, DPP lane reduction; plus pooling-history batch copy and phase-0 gain deferral
# speedup vs baseline: 1.0557x; 1.0218x over previous
.LBB0_152:
	s_and_b64 vcc, exec, s[2:3]
	s_cbranch_vccz .LBB0_249
	v_readlane_b32 s54, v255, 2
	s_bitcmp0_b32 s54, 0
	s_cselect_b64 s[0:1], -1, 0
	v_readlane_b32 s55, v255, 3
	v_writelane_b32 v255, s0, 14
	v_readlane_b32 s50, v254, 17
	v_readlane_b32 s56, v254, 56
	v_writelane_b32 v255, s1, 15
	s_and_b64 vcc, exec, s[0:1]
	v_readlane_b32 s51, v254, 18
	v_readlane_b32 s52, v254, 62
	v_readlane_b32 s57, v254, 57
	v_readlane_b32 s53, v254, 63
	s_cbranch_vccnz .LBB0_184
	s_mov_b32 s48, 0
.Lss_entry:
	v_readlane_b32 s22, v255, 2
	v_readlane_b32 s23, v254, 62
	v_readlane_b32 s0, v254, 56
	v_readlane_b32 s1, v254, 57
	s_cmpk_lt_i32 s22, 0x800
	s_cbranch_scc0 .Lss_ret
	s_load_dwordx2 s[4:5], s[0:1], 0x18
	s_load_dwordx4 s[12:15], s[0:1], 0x70
	s_load_dwordx2 s[6:7], s[0:1], 0x100
	s_load_dwordx2 s[8:9], s[0:1], 0x108
	v_lshlrev_b32_e32 v1, 6, v174
	v_and_b32_e32 v11, 7, v174
	v_lshlrev_b32_e32 v2, 5, v11
	v_cmp_eq_u32_e64 s[38:39], 0, v11
	v_lshrrev_b32_e32 v12, 3, v174
	v_lshlrev_b32_e32 v4, 1, v12
	v_add_u32_e32 v3, 0x200, v4
	v_add_u32_e32 v5, 0x1000, v4
	s_movk_i32 s2, 0xa0
	v_cmp_gt_u32_e64 s[46:47], s2, v174
	v_mul_u32_u24_e32 v11, 0xcd, v174
	v_lshrrev_b32_e32 v11, 13, v11
	v_mul_u32_u24_e32 v12, 40, v11
	v_sub_u32_e32 v12, v174, v12
	v_mul_u32_u24_e32 v6, 0xc00, v11
	v_lshl_add_u32 v6, v12, 4, v6
	v_lshlrev_b32_e32 v7, 4, v174
	v_cmp_gt_u32_e32 vcc, 32, v12
	v_mov_b32_e32 v13, 0x100
	v_mov_b32_e32 v14, 0x80
	v_cndmask_b32_e32 v8, 0, v13, vcc
	v_cndmask_b32_e32 v9, v14, v26, vcc
	v_mov_b32_e32 v13, 0x900
	v_mov_b32_e32 v14, 0xfffffe00
	v_cndmask_b32_e32 v14, v14, v13, vcc
	v_cmp_gt_u32_e32 vcc, 16, v12
	v_mov_b32_e32 v13, 0x800
	s_nop 0
	v_cndmask_b32_e32 v14, v14, v13, vcc
	v_add_u32_e32 v6, v6, v14
	s_waitcnt lgkmcnt(0)
	s_mov_b64 s[18:19], s[14:15]
	s_mov_b64 s[14:15], s[12:13]
	s_add_u32 s6, s6, 0x4600000
	s_addc_u32 s7, s7, 0
	s_add_u32 s10, s8, 0x5200000
	s_addc_u32 s11, s9, 0
	s_add_u32 s12, s8, 0x17a08000
	s_addc_u32 s13, s9, 0
	s_add_u32 s8, s8, 0x13788000
	s_addc_u32 s9, s9, 0
	s_mov_b32 s24, s22
	s_lshr_b32 s25, s24, 4
	s_and_b32 s26, s24, 15
	s_lshr_b32 s27, s26, 3
	s_lshl_b32 s2, s25, 8
	s_lshl_b32 s3, s26, 2
	s_add_u32 s2, s2, s3
	s_add_u32 s0, s10, s2
	s_addc_u32 s1, s11, 0
	s_load_dword s40, s[0:1], 0x0
	s_load_dword s41, s[0:1], 0x40
	s_load_dword s42, s[0:1], 0x80
	s_load_dword s43, s[0:1], 0xc0
	s_add_u32 s0, s14, s3
	s_addc_u32 s1, s15, 0
	s_load_dword s44, s[0:1], 0x0
	s_add_u32 s0, s18, s3
	s_addc_u32 s1, s19, 0
	s_load_dword s45, s[0:1], 0x0
	s_mul_i32 s2, s25, 0x3000
	s_add_u32 s36, s8, s2
	s_addc_u32 s37, s9, 0
	s_lshl_b32 s2, s24, 15
	s_add_u32 s34, s4, s2
	s_addc_u32 s35, s5, 0
	v_mad_u32_u24 v10, s27, v8, v6
	v_mad_u32_u24 v10, s26, v9, v10
	s_mov_b64 s[0:1], exec
	s_and_b64 exec, exec, s[46:47]
	s_cbranch_execz .Lss_nostg_pro
	global_load_dwordx4 v[16:19], v10, s[36:37]
.Lss_nostg_pro:
	s_mov_b64 exec, s[0:1]
	global_load_dwordx4 v[44:47], v1, s[34:35] offset:48 nt
	global_load_dwordx4 v[40:43], v1, s[34:35] offset:32 nt
	global_load_dwordx4 v[36:39], v1, s[34:35] offset:16 nt
	global_load_dwordx4 v[32:35], v1, s[34:35] nt
	s_waitcnt vmcnt(4)
	s_mov_b64 s[0:1], exec
	s_and_b64 exec, exec, s[46:47]
	s_cbranch_execz .Lss_nowr_pro
	ds_write_b128 v7, v[16:19]
.Lss_nowr_pro:
	s_mov_b64 exec, s[0:1]
.Lss_loop:
	s_waitcnt lgkmcnt(0)
	s_barrier
	v_mov_b32_e32 v20, s40
	v_mov_b32_e32 v21, s41
	v_mov_b32_e32 v22, s42
	v_mov_b32_e32 v23, s43
	v_mov_b32_e32 v12, s44
	v_mov_b32_e32 v25, s45
	s_lshl_b32 s2, s22, 15
	s_add_u32 s28, s6, s2
	s_addc_u32 s29, s7, 0
	s_lshr_b32 s25, s22, 4
	s_and_b32 s26, s22, 15
	s_lshl_b32 s2, s25, 13
	s_lshl_b32 s3, s26, 7
	s_add_u32 s2, s2, s3
	s_add_u32 s30, s12, s2
	s_addc_u32 s31, s13, 0
	s_add_i32 s24, s22, s23
	s_cmpk_lt_i32 s24, 0x800
	s_cselect_b32 s33, 1, 0
	s_cbranch_scc0 .Lss_nonext_a
	s_lshr_b32 s25, s24, 4
	s_and_b32 s26, s24, 15
	s_lshr_b32 s27, s26, 3
	s_lshl_b32 s2, s25, 8
	s_lshl_b32 s3, s26, 2
	s_add_u32 s2, s2, s3
	s_add_u32 s0, s10, s2
	s_addc_u32 s1, s11, 0
	s_load_dword s40, s[0:1], 0x0
	s_load_dword s41, s[0:1], 0x40
	s_load_dword s42, s[0:1], 0x80
	s_load_dword s43, s[0:1], 0xc0
	s_add_u32 s0, s14, s3
	s_addc_u32 s1, s15, 0
	s_load_dword s44, s[0:1], 0x0
	s_add_u32 s0, s18, s3
	s_addc_u32 s1, s19, 0
	s_load_dword s45, s[0:1], 0x0
	s_mul_i32 s2, s25, 0x3000
	s_add_u32 s36, s8, s2
	s_addc_u32 s37, s9, 0
	s_lshl_b32 s2, s24, 15
	s_add_u32 s34, s4, s2
	s_addc_u32 s35, s5, 0
	v_mad_u32_u24 v10, s27, v8, v6
	v_mad_u32_u24 v10, s26, v9, v10
	s_mov_b64 s[0:1], exec
	s_and_b64 exec, exec, s[46:47]
	s_cbranch_execz .Lss_nostg_a
	global_load_dwordx4 v[16:19], v10, s[36:37]
.Lss_nostg_a:
	s_mov_b64 exec, s[0:1]
	global_load_dwordx4 v[60:63], v1, s[34:35] offset:48 nt
	global_load_dwordx4 v[56:59], v1, s[34:35] offset:32 nt
	global_load_dwordx4 v[52:55], v1, s[34:35] offset:16 nt
	global_load_dwordx4 v[48:51], v1, s[34:35] nt
.Lss_nonext_a:
	ds_read_b128 v[64:67], v2
	ds_read_b128 v[68:71], v2 offset:16
	ds_read_b128 v[72:75], v2 offset:256
	ds_read_b128 v[76:79], v2 offset:272
	ds_read_u16 v128, v3
	ds_read_b128 v[80:83], v2 offset:640
	ds_read_b128 v[84:87], v2 offset:656
	v_mul_f32_e32 v11, 0x3fb8aa3b, v12
	s_mov_b32 s2, 0x3fb8aa3b
	v_fma_f32 v13, v12, s2, -v11
	v_rndne_f32_e32 v14, v11
	v_fmac_f32_e32 v13, 0x32a5705f, v12
	v_sub_f32_e32 v11, v11, v14
	v_add_f32_e32 v11, v11, v13
	v_exp_f32_e32 v24, v11
	v_cvt_i32_f32_e32 v14, v14
	s_nop 0
	v_ldexp_f32 v24, v24, v14
	v_cmp_ngt_f32_e32 vcc, 0xc2ce8ed0, v12
	s_nop 1
	v_cndmask_b32_e32 v24, 0, v24, vcc
	v_cmp_nlt_f32_e32 vcc, 0x42b17218, v12
	s_nop 1
	v_cndmask_b32_e32 v24, v231, v24, vcc
	s_cmp_eq_u32 s33, 0
	s_cbranch_scc1 .Lss_w0_a
	s_waitcnt vmcnt(4)
	s_branch .Lss_w1_a

.Lss_w1_a:
	s_waitcnt lgkmcnt(0)
	ds_read_b128 v[88:91], v2 offset:896
	ds_read_b128 v[92:95], v2 offset:912
	ds_read_u16 v129, v3 offset:640
	ds_read_b128 v[96:99], v2 offset:1280
	ds_read_b128 v[100:103], v2 offset:1296
	ds_read_b128 v[104:107], v2 offset:1536
	ds_read_b128 v[108:111], v2 offset:1552
	ds_read_u16 v130, v3 offset:1280
	ds_read_b128 v[112:115], v2 offset:1920
	ds_read_b128 v[116:119], v2 offset:1936
	ds_read_b128 v[120:123], v2 offset:2176
	ds_read_b128 v[124:127], v2 offset:2192
	ds_read_u16 v131, v3 offset:1920
	v_lshlrev_b32_e32 v140, 16, v128
	v_mul_f32_e32 v11, v20, v24
	v_mul_f32_e32 v11, 0xbfb8aa3b, v11
	v_exp_f32_e32 v28, v11
	v_mul_f32_e32 v30, v20, v140
	v_lshlrev_b32_e32 v132, 16, v64
	v_and_b32_e32 v133, 0xffff0000, v64
	v_pk_mul_f32 v[32:33], v[32:33], v[28:29] op_sel_hi:[1,0]
	v_lshlrev_b32_e32 v136, 16, v72
	v_and_b32_e32 v137, 0xffff0000, v72
	v_pk_fma_f32 v[32:33], v[30:31], v[132:133], v[32:33] op_sel_hi:[0,1,1]
	v_fma_f32 v144, v32, v136, 0
	v_fmac_f32_e32 v144, v33, v137
	v_lshlrev_b32_e32 v134, 16, v65
	v_and_b32_e32 v135, 0xffff0000, v65
	v_pk_mul_f32 v[34:35], v[34:35], v[28:29] op_sel_hi:[1,0]
	v_lshlrev_b32_e32 v138, 16, v73
	v_and_b32_e32 v139, 0xffff0000, v73
	v_pk_fma_f32 v[34:35], v[30:31], v[134:135], v[34:35] op_sel_hi:[0,1,1]
	v_fmac_f32_e32 v144, v34, v138
	v_fmac_f32_e32 v144, v35, v139
	v_lshlrev_b32_e32 v132, 16, v66
	v_and_b32_e32 v133, 0xffff0000, v66
	v_pk_mul_f32 v[36:37], v[36:37], v[28:29] op_sel_hi:[1,0]
	v_lshlrev_b32_e32 v136, 16, v74
	v_and_b32_e32 v137, 0xffff0000, v74
	v_pk_fma_f32 v[36:37], v[30:31], v[132:133], v[36:37] op_sel_hi:[0,1,1]
	v_fmac_f32_e32 v144, v36, v136
	v_fmac_f32_e32 v144, v37, v137
	v_lshlrev_b32_e32 v134, 16, v67
	v_and_b32_e32 v135, 0xffff0000, v67
	v_pk_mul_f32 v[38:39], v[38:39], v[28:29] op_sel_hi:[1,0]
	v_lshlrev_b32_e32 v138, 16, v75
	v_and_b32_e32 v139, 0xffff0000, v75
	v_pk_fma_f32 v[38:39], v[30:31], v[134:135], v[38:39] op_sel_hi:[0,1,1]
	v_fmac_f32_e32 v144, v38, v138
	v_fmac_f32_e32 v144, v39, v139
	v_lshlrev_b32_e32 v132, 16, v68
	v_and_b32_e32 v133, 0xffff0000, v68
	v_pk_mul_f32 v[40:41], v[40:41], v[28:29] op_sel_hi:[1,0]
	v_lshlrev_b32_e32 v136, 16, v76
	v_and_b32_e32 v137, 0xffff0000, v76
	v_pk_fma_f32 v[40:41], v[30:31], v[132:133], v[40:41] op_sel_hi:[0,1,1]
	v_fmac_f32_e32 v144, v40, v136
	v_fmac_f32_e32 v144, v41, v137
	v_lshlrev_b32_e32 v134, 16, v69
	v_and_b32_e32 v135, 0xffff0000, v69
	v_pk_mul_f32 v[42:43], v[42:43], v[28:29] op_sel_hi:[1,0]
	v_lshlrev_b32_e32 v138, 16, v77
	v_and_b32_e32 v139, 0xffff0000, v77
	v_pk_fma_f32 v[42:43], v[30:31], v[134:135], v[42:43] op_sel_hi:[0,1,1]
	v_fmac_f32_e32 v144, v42, v138
	v_fmac_f32_e32 v144, v43, v139
	v_lshlrev_b32_e32 v132, 16, v70
	v_and_b32_e32 v133, 0xffff0000, v70
	v_pk_mul_f32 v[44:45], v[44:45], v[28:29] op_sel_hi:[1,0]
	v_lshlrev_b32_e32 v136, 16, v78
	v_and_b32_e32 v137, 0xffff0000, v78
	v_pk_fma_f32 v[44:45], v[30:31], v[132:133], v[44:45] op_sel_hi:[0,1,1]
	v_fmac_f32_e32 v144, v44, v136
	v_fmac_f32_e32 v144, v45, v137
	v_lshlrev_b32_e32 v134, 16, v71
	v_and_b32_e32 v135, 0xffff0000, v71
	v_pk_mul_f32 v[46:47], v[46:47], v[28:29] op_sel_hi:[1,0]
	v_lshlrev_b32_e32 v138, 16, v79
	v_and_b32_e32 v139, 0xffff0000, v79
	v_pk_fma_f32 v[46:47], v[30:31], v[134:135], v[46:47] op_sel_hi:[0,1,1]
	v_fmac_f32_e32 v144, v46, v138
	v_fmac_f32_e32 v144, v47, v139
	s_nop 1
	v_add_f32_dpp v144, v144, v144 quad_perm:[1,0,3,2] row_mask:0xf bank_mask:0xf
	s_nop 1
	v_add_f32_dpp v144, v144, v144 quad_perm:[2,3,0,1] row_mask:0xf bank_mask:0xf
	s_nop 1
	v_add_f32_dpp v144, v144, v144 row_shl:4 row_mask:0xf bank_mask:0xf
	s_nop 1
	v_fmac_f32_e32 v144, v25, v140
	v_cvt_pk_bf16_f32 v144, v144, v26
	s_waitcnt lgkmcnt(0)
	v_lshlrev_b32_e32 v141, 16, v129
	v_mul_f32_e32 v11, v21, v24
	v_mul_f32_e32 v11, 0xbfb8aa3b, v11
	v_exp_f32_e32 v28, v11
	v_mul_f32_e32 v30, v21, v141
	v_lshlrev_b32_e32 v132, 16, v80
	v_and_b32_e32 v133, 0xffff0000, v80
	v_pk_mul_f32 v[32:33], v[32:33], v[28:29] op_sel_hi:[1,0]
	v_lshlrev_b32_e32 v136, 16, v88
	v_and_b32_e32 v137, 0xffff0000, v88
	v_pk_fma_f32 v[32:33], v[30:31], v[132:133], v[32:33] op_sel_hi:[0,1,1]
	v_fma_f32 v145, v32, v136, 0
	v_fmac_f32_e32 v145, v33, v137
	v_lshlrev_b32_e32 v134, 16, v81
	v_and_b32_e32 v135, 0xffff0000, v81
	v_pk_mul_f32 v[34:35], v[34:35], v[28:29] op_sel_hi:[1,0]
	v_lshlrev_b32_e32 v138, 16, v89
	v_and_b32_e32 v139, 0xffff0000, v89
	v_pk_fma_f32 v[34:35], v[30:31], v[134:135], v[34:35] op_sel_hi:[0,1,1]
	v_fmac_f32_e32 v145, v34, v138
	v_fmac_f32_e32 v145, v35, v139
	v_lshlrev_b32_e32 v132, 16, v82
	v_and_b32_e32 v133, 0xffff0000, v82
	v_pk_mul_f32 v[36:37], v[36:37], v[28:29] op_sel_hi:[1,0]
	v_lshlrev_b32_e32 v136, 16, v90
	v_and_b32_e32 v137, 0xffff0000, v90
	v_pk_fma_f32 v[36:37], v[30:31], v[132:133], v[36:37] op_sel_hi:[0,1,1]
	v_fmac_f32_e32 v145, v36, v136
	v_fmac_f32_e32 v145, v37, v137
	v_lshlrev_b32_e32 v134, 16, v83
	v_and_b32_e32 v135, 0xffff0000, v83
	v_pk_mul_f32 v[38:39], v[38:39], v[28:29] op_sel_hi:[1,0]
	v_lshlrev_b32_e32 v138, 16, v91
	v_and_b32_e32 v139, 0xffff0000, v91
	v_pk_fma_f32 v[38:39], v[30:31], v[134:135], v[38:39] op_sel_hi:[0,1,1]
	v_fmac_f32_e32 v145, v38, v138
	v_fmac_f32_e32 v145, v39, v139
	v_lshlrev_b32_e32 v132, 16, v84
	v_and_b32_e32 v133, 0xffff0000, v84
	v_pk_mul_f32 v[40:41], v[40:41], v[28:29] op_sel_hi:[1,0]
	v_lshlrev_b32_e32 v136, 16, v92
	v_and_b32_e32 v137, 0xffff0000, v92
	v_pk_fma_f32 v[40:41], v[30:31], v[132:133], v[40:41] op_sel_hi:[0,1,1]
	v_fmac_f32_e32 v145, v40, v136
	v_fmac_f32_e32 v145, v41, v137
	v_lshlrev_b32_e32 v134, 16, v85
	v_and_b32_e32 v135, 0xffff0000, v85
	v_pk_mul_f32 v[42:43], v[42:43], v[28:29] op_sel_hi:[1,0]
	v_lshlrev_b32_e32 v138, 16, v93
	v_and_b32_e32 v139, 0xffff0000, v93
	v_pk_fma_f32 v[42:43], v[30:31], v[134:135], v[42:43] op_sel_hi:[0,1,1]
	v_fmac_f32_e32 v145, v42, v138
	v_fmac_f32_e32 v145, v43, v139
	v_lshlrev_b32_e32 v132, 16, v86
	v_and_b32_e32 v133, 0xffff0000, v86
	v_pk_mul_f32 v[44:45], v[44:45], v[28:29] op_sel_hi:[1,0]
	v_lshlrev_b32_e32 v136, 16, v94
	v_and_b32_e32 v137, 0xffff0000, v94
	v_pk_fma_f32 v[44:45], v[30:31], v[132:133], v[44:45] op_sel_hi:[0,1,1]
	v_fmac_f32_e32 v145, v44, v136
	v_fmac_f32_e32 v145, v45, v137
	v_lshlrev_b32_e32 v134, 16, v87
	v_and_b32_e32 v135, 0xffff0000, v87
	v_pk_mul_f32 v[46:47], v[46:47], v[28:29] op_sel_hi:[1,0]
	v_lshlrev_b32_e32 v138, 16, v95
	v_and_b32_e32 v139, 0xffff0000, v95
	v_pk_fma_f32 v[46:47], v[30:31], v[134:135], v[46:47] op_sel_hi:[0,1,1]
	v_fmac_f32_e32 v145, v46, v138
	v_fmac_f32_e32 v145, v47, v139
	s_nop 1
	v_add_f32_dpp v145, v145, v145 quad_perm:[1,0,3,2] row_mask:0xf bank_mask:0xf
	s_nop 1
	v_add_f32_dpp v145, v145, v145 quad_perm:[2,3,0,1] row_mask:0xf bank_mask:0xf
	s_nop 1
	v_add_f32_dpp v145, v145, v145 row_shl:4 row_mask:0xf bank_mask:0xf
	s_nop 1
	v_fmac_f32_e32 v145, v25, v141
	v_cvt_pk_bf16_f32 v145, v145, v26
	v_lshlrev_b32_e32 v142, 16, v130
	v_mul_f32_e32 v11, v22, v24
	v_mul_f32_e32 v11, 0xbfb8aa3b, v11
	v_exp_f32_e32 v28, v11
	v_mul_f32_e32 v30, v22, v142
	v_lshlrev_b32_e32 v132, 16, v96
	v_and_b32_e32 v133, 0xffff0000, v96
	v_pk_mul_f32 v[32:33], v[32:33], v[28:29] op_sel_hi:[1,0]
	v_lshlrev_b32_e32 v136, 16, v104
	v_and_b32_e32 v137, 0xffff0000, v104
	v_pk_fma_f32 v[32:33], v[30:31], v[132:133], v[32:33] op_sel_hi:[0,1,1]
	v_fma_f32 v146, v32, v136, 0
	v_fmac_f32_e32 v146, v33, v137
	v_lshlrev_b32_e32 v134, 16, v97
	v_and_b32_e32 v135, 0xffff0000, v97
	v_pk_mul_f32 v[34:35], v[34:35], v[28:29] op_sel_hi:[1,0]
	v_lshlrev_b32_e32 v138, 16, v105
	v_and_b32_e32 v139, 0xffff0000, v105
	v_pk_fma_f32 v[34:35], v[30:31], v[134:135], v[34:35] op_sel_hi:[0,1,1]
	v_fmac_f32_e32 v146, v34, v138
	v_fmac_f32_e32 v146, v35, v139
	v_lshlrev_b32_e32 v132, 16, v98
	v_and_b32_e32 v133, 0xffff0000, v98
	v_pk_mul_f32 v[36:37], v[36:37], v[28:29] op_sel_hi:[1,0]
	v_lshlrev_b32_e32 v136, 16, v106
	v_and_b32_e32 v137, 0xffff0000, v106
	v_pk_fma_f32 v[36:37], v[30:31], v[132:133], v[36:37] op_sel_hi:[0,1,1]
	v_fmac_f32_e32 v146, v36, v136
	v_fmac_f32_e32 v146, v37, v137
	v_lshlrev_b32_e32 v134, 16, v99
	v_and_b32_e32 v135, 0xffff0000, v99
	v_pk_mul_f32 v[38:39], v[38:39], v[28:29] op_sel_hi:[1,0]
	v_lshlrev_b32_e32 v138, 16, v107
	v_and_b32_e32 v139, 0xffff0000, v107
	v_pk_fma_f32 v[38:39], v[30:31], v[134:135], v[38:39] op_sel_hi:[0,1,1]
	v_fmac_f32_e32 v146, v38, v138
	v_fmac_f32_e32 v146, v39, v139
	v_lshlrev_b32_e32 v132, 16, v100
	v_and_b32_e32 v133, 0xffff0000, v100
	v_pk_mul_f32 v[40:41], v[40:41], v[28:29] op_sel_hi:[1,0]
	v_lshlrev_b32_e32 v136, 16, v108
	v_and_b32_e32 v137, 0xffff0000, v108
	v_pk_fma_f32 v[40:41], v[30:31], v[132:133], v[40:41] op_sel_hi:[0,1,1]
	v_fmac_f32_e32 v146, v40, v136
	v_fmac_f32_e32 v146, v41, v137
	v_lshlrev_b32_e32 v134, 16, v101
	v_and_b32_e32 v135, 0xffff0000, v101
	v_pk_mul_f32 v[42:43], v[42:43], v[28:29] op_sel_hi:[1,0]
	v_lshlrev_b32_e32 v138, 16, v109
	v_and_b32_e32 v139, 0xffff0000, v109
	v_pk_fma_f32 v[42:43], v[30:31], v[134:135], v[42:43] op_sel_hi:[0,1,1]
	v_fmac_f32_e32 v146, v42, v138
	v_fmac_f32_e32 v146, v43, v139
	v_lshlrev_b32_e32 v132, 16, v102
	v_and_b32_e32 v133, 0xffff0000, v102
	v_pk_mul_f32 v[44:45], v[44:45], v[28:29] op_sel_hi:[1,0]
	v_lshlrev_b32_e32 v136, 16, v110
	v_and_b32_e32 v137, 0xffff0000, v110
	v_pk_fma_f32 v[44:45], v[30:31], v[132:133], v[44:45] op_sel_hi:[0,1,1]
	v_fmac_f32_e32 v146, v44, v136
	v_fmac_f32_e32 v146, v45, v137
	v_lshlrev_b32_e32 v134, 16, v103
	v_and_b32_e32 v135, 0xffff0000, v103
	v_pk_mul_f32 v[46:47], v[46:47], v[28:29] op_sel_hi:[1,0]
	v_lshlrev_b32_e32 v138, 16, v111
	v_and_b32_e32 v139, 0xffff0000, v111
	v_pk_fma_f32 v[46:47], v[30:31], v[134:135], v[46:47] op_sel_hi:[0,1,1]
	v_fmac_f32_e32 v146, v46, v138
	v_fmac_f32_e32 v146, v47, v139
	s_nop 1
	v_add_f32_dpp v146, v146, v146 quad_perm:[1,0,3,2] row_mask:0xf bank_mask:0xf
	s_nop 1
	v_add_f32_dpp v146, v146, v146 quad_perm:[2,3,0,1] row_mask:0xf bank_mask:0xf
	s_nop 1
	v_add_f32_dpp v146, v146, v146 row_shl:4 row_mask:0xf bank_mask:0xf
	s_nop 1
	v_fmac_f32_e32 v146, v25, v142
	v_cvt_pk_bf16_f32 v146, v146, v26
	v_lshlrev_b32_e32 v143, 16, v131
	v_mul_f32_e32 v11, v23, v24
	v_mul_f32_e32 v11, 0xbfb8aa3b, v11
	v_exp_f32_e32 v28, v11
	v_mul_f32_e32 v30, v23, v143
	v_lshlrev_b32_e32 v132, 16, v112
	v_and_b32_e32 v133, 0xffff0000, v112
	v_pk_mul_f32 v[32:33], v[32:33], v[28:29] op_sel_hi:[1,0]
	v_lshlrev_b32_e32 v136, 16, v120
	v_and_b32_e32 v137, 0xffff0000, v120
	v_pk_fma_f32 v[32:33], v[30:31], v[132:133], v[32:33] op_sel_hi:[0,1,1]
	v_fma_f32 v147, v32, v136, 0
	v_fmac_f32_e32 v147, v33, v137
	v_lshlrev_b32_e32 v134, 16, v113
	v_and_b32_e32 v135, 0xffff0000, v113
	v_pk_mul_f32 v[34:35], v[34:35], v[28:29] op_sel_hi:[1,0]
	v_lshlrev_b32_e32 v138, 16, v121
	v_and_b32_e32 v139, 0xffff0000, v121
	v_pk_fma_f32 v[34:35], v[30:31], v[134:135], v[34:35] op_sel_hi:[0,1,1]
	v_fmac_f32_e32 v147, v34, v138
	v_fmac_f32_e32 v147, v35, v139
	v_lshlrev_b32_e32 v132, 16, v114
	v_and_b32_e32 v133, 0xffff0000, v114
	v_pk_mul_f32 v[36:37], v[36:37], v[28:29] op_sel_hi:[1,0]
	v_lshlrev_b32_e32 v136, 16, v122
	v_and_b32_e32 v137, 0xffff0000, v122
	v_pk_fma_f32 v[36:37], v[30:31], v[132:133], v[36:37] op_sel_hi:[0,1,1]
	v_fmac_f32_e32 v147, v36, v136
	v_fmac_f32_e32 v147, v37, v137
	v_lshlrev_b32_e32 v134, 16, v115
	v_and_b32_e32 v135, 0xffff0000, v115
	v_pk_mul_f32 v[38:39], v[38:39], v[28:29] op_sel_hi:[1,0]
	v_lshlrev_b32_e32 v138, 16, v123
	v_and_b32_e32 v139, 0xffff0000, v123
	v_pk_fma_f32 v[38:39], v[30:31], v[134:135], v[38:39] op_sel_hi:[0,1,1]
	v_fmac_f32_e32 v147, v38, v138
	v_fmac_f32_e32 v147, v39, v139
	v_lshlrev_b32_e32 v132, 16, v116
	v_and_b32_e32 v133, 0xffff0000, v116
	v_pk_mul_f32 v[40:41], v[40:41], v[28:29] op_sel_hi:[1,0]
	v_lshlrev_b32_e32 v136, 16, v124
	v_and_b32_e32 v137, 0xffff0000, v124
	v_pk_fma_f32 v[40:41], v[30:31], v[132:133], v[40:41] op_sel_hi:[0,1,1]
	v_fmac_f32_e32 v147, v40, v136
	v_fmac_f32_e32 v147, v41, v137
	v_lshlrev_b32_e32 v134, 16, v117
	v_and_b32_e32 v135, 0xffff0000, v117
	v_pk_mul_f32 v[42:43], v[42:43], v[28:29] op_sel_hi:[1,0]
	v_lshlrev_b32_e32 v138, 16, v125
	v_and_b32_e32 v139, 0xffff0000, v125
	v_pk_fma_f32 v[42:43], v[30:31], v[134:135], v[42:43] op_sel_hi:[0,1,1]
	v_fmac_f32_e32 v147, v42, v138
	v_fmac_f32_e32 v147, v43, v139
	v_lshlrev_b32_e32 v132, 16, v118
	v_and_b32_e32 v133, 0xffff0000, v118
	v_pk_mul_f32 v[44:45], v[44:45], v[28:29] op_sel_hi:[1,0]
	v_lshlrev_b32_e32 v136, 16, v126
	v_and_b32_e32 v137, 0xffff0000, v126
	v_pk_fma_f32 v[44:45], v[30:31], v[132:133], v[44:45] op_sel_hi:[0,1,1]
	v_fmac_f32_e32 v147, v44, v136
	v_fmac_f32_e32 v147, v45, v137
	v_lshlrev_b32_e32 v134, 16, v119
	v_and_b32_e32 v135, 0xffff0000, v119
	v_pk_mul_f32 v[46:47], v[46:47], v[28:29] op_sel_hi:[1,0]
	v_lshlrev_b32_e32 v138, 16, v127
	v_and_b32_e32 v139, 0xffff0000, v127
	v_pk_fma_f32 v[46:47], v[30:31], v[134:135], v[46:47] op_sel_hi:[0,1,1]
	v_fmac_f32_e32 v147, v46, v138
	v_fmac_f32_e32 v147, v47, v139
	s_nop 1
	v_add_f32_dpp v147, v147, v147 quad_perm:[1,0,3,2] row_mask:0xf bank_mask:0xf
	s_nop 1
	v_add_f32_dpp v147, v147, v147 quad_perm:[2,3,0,1] row_mask:0xf bank_mask:0xf
	s_nop 1
	v_add_f32_dpp v147, v147, v147 row_shl:4 row_mask:0xf bank_mask:0xf
	s_nop 1
	v_fmac_f32_e32 v147, v25, v143
	v_cvt_pk_bf16_f32 v147, v147, v26
	s_mov_b64 s[0:1], exec
	s_and_b64 exec, exec, s[38:39]
	global_store_short v4, v144, s[30:31]
	global_store_short v4, v145, s[30:31] offset:2048
	global_store_short v5, v146, s[30:31]
	global_store_short v5, v147, s[30:31] offset:2048
	s_mov_b64 exec, s[0:1]
	global_store_dwordx4 v1, v[32:35], s[28:29] nt
	global_store_dwordx4 v1, v[36:39], s[28:29] offset:16 nt
	global_store_dwordx4 v1, v[40:43], s[28:29] offset:32 nt
	global_store_dwordx4 v1, v[44:47], s[28:29] offset:48 nt
	s_cmp_eq_u32 s33, 0
	s_cbranch_scc1 .Lss_exit
	s_waitcnt vmcnt(12)
	s_mov_b64 s[0:1], exec
	s_and_b64 exec, exec, s[46:47]
	s_cbranch_execz .Lss_nowr_a
	ds_write_b128 v7, v[16:19] offset:4096
.Lss_nowr_a:
	s_mov_b64 exec, s[0:1]
	s_mov_b32 s22, s24
	s_waitcnt lgkmcnt(0)
	s_barrier
	v_mov_b32_e32 v20, s40
	v_mov_b32_e32 v21, s41
	v_mov_b32_e32 v22, s42
	v_mov_b32_e32 v23, s43
	v_mov_b32_e32 v12, s44
	v_mov_b32_e32 v25, s45
	s_lshl_b32 s2, s22, 15
	s_add_u32 s28, s6, s2
	s_addc_u32 s29, s7, 0
	s_lshr_b32 s25, s22, 4
	s_and_b32 s26, s22, 15
	s_lshl_b32 s2, s25, 13
	s_lshl_b32 s3, s26, 7
	s_add_u32 s2, s2, s3
	s_add_u32 s30, s12, s2
	s_addc_u32 s31, s13, 0
	s_add_i32 s24, s22, s23
	s_cmpk_lt_i32 s24, 0x800
	s_cselect_b32 s33, 1, 0
	s_cbranch_scc0 .Lss_nonext_b
	s_lshr_b32 s25, s24, 4
	s_and_b32 s26, s24, 15
	s_lshr_b32 s27, s26, 3
	s_lshl_b32 s2, s25, 8
	s_lshl_b32 s3, s26, 2
	s_add_u32 s2, s2, s3
	s_add_u32 s0, s10, s2
	s_addc_u32 s1, s11, 0
	s_load_dword s40, s[0:1], 0x0
	s_load_dword s41, s[0:1], 0x40
	s_load_dword s42, s[0:1], 0x80
	s_load_dword s43, s[0:1], 0xc0
	s_add_u32 s0, s14, s3
	s_addc_u32 s1, s15, 0
	s_load_dword s44, s[0:1], 0x0
	s_add_u32 s0, s18, s3
	s_addc_u32 s1, s19, 0
	s_load_dword s45, s[0:1], 0x0
	s_mul_i32 s2, s25, 0x3000
	s_add_u32 s36, s8, s2
	s_addc_u32 s37, s9, 0
	s_lshl_b32 s2, s24, 15
	s_add_u32 s34, s4, s2
	s_addc_u32 s35, s5, 0
	v_mad_u32_u24 v10, s27, v8, v6
	v_mad_u32_u24 v10, s26, v9, v10
	s_mov_b64 s[0:1], exec
	s_and_b64 exec, exec, s[46:47]
	s_cbranch_execz .Lss_nostg_b
	global_load_dwordx4 v[16:19], v10, s[36:37]
.Lss_nostg_b:
	s_mov_b64 exec, s[0:1]
	global_load_dwordx4 v[44:47], v1, s[34:35] offset:48 nt
	global_load_dwordx4 v[40:43], v1, s[34:35] offset:32 nt
	global_load_dwordx4 v[36:39], v1, s[34:35] offset:16 nt
	global_load_dwordx4 v[32:35], v1, s[34:35] nt
.Lss_nonext_b:
	ds_read_b128 v[64:67], v2 offset:4096
	ds_read_b128 v[68:71], v2 offset:4112
	ds_read_b128 v[72:75], v2 offset:4352
	ds_read_b128 v[76:79], v2 offset:4368
	ds_read_u16 v128, v3 offset:4096
	ds_read_b128 v[80:83], v2 offset:4736
	ds_read_b128 v[84:87], v2 offset:4752
	v_mul_f32_e32 v11, 0x3fb8aa3b, v12
	s_mov_b32 s2, 0x3fb8aa3b
	v_fma_f32 v13, v12, s2, -v11
	v_rndne_f32_e32 v14, v11
	v_fmac_f32_e32 v13, 0x32a5705f, v12
	v_sub_f32_e32 v11, v11, v14
	v_add_f32_e32 v11, v11, v13
	v_exp_f32_e32 v24, v11
	v_cvt_i32_f32_e32 v14, v14
	s_nop 0
	v_ldexp_f32 v24, v24, v14
	v_cmp_ngt_f32_e32 vcc, 0xc2ce8ed0, v12
	s_nop 1
	v_cndmask_b32_e32 v24, 0, v24, vcc
	v_cmp_nlt_f32_e32 vcc, 0x42b17218, v12
	s_nop 1
	v_cndmask_b32_e32 v24, v231, v24, vcc
	s_cmp_eq_u32 s33, 0
	s_cbranch_scc1 .Lss_w0_b
	s_waitcnt vmcnt(4)
	s_branch .Lss_w1_b

.Lss_w1_b:
	s_waitcnt lgkmcnt(0)
	ds_read_b128 v[88:91], v2 offset:4992
	ds_read_b128 v[92:95], v2 offset:5008
	ds_read_u16 v129, v3 offset:4736
	ds_read_b128 v[96:99], v2 offset:5376
	ds_read_b128 v[100:103], v2 offset:5392
	ds_read_b128 v[104:107], v2 offset:5632
	ds_read_b128 v[108:111], v2 offset:5648
	ds_read_u16 v130, v3 offset:5376
	ds_read_b128 v[112:115], v2 offset:6016
	ds_read_b128 v[116:119], v2 offset:6032
	ds_read_b128 v[120:123], v2 offset:6272
	ds_read_b128 v[124:127], v2 offset:6288
	ds_read_u16 v131, v3 offset:6016
	v_lshlrev_b32_e32 v140, 16, v128
	v_mul_f32_e32 v11, v20, v24
	v_mul_f32_e32 v11, 0xbfb8aa3b, v11
	v_exp_f32_e32 v28, v11
	v_mul_f32_e32 v30, v20, v140
	v_lshlrev_b32_e32 v132, 16, v64
	v_and_b32_e32 v133, 0xffff0000, v64
	v_pk_mul_f32 v[48:49], v[48:49], v[28:29] op_sel_hi:[1,0]
	v_lshlrev_b32_e32 v136, 16, v72
	v_and_b32_e32 v137, 0xffff0000, v72
	v_pk_fma_f32 v[48:49], v[30:31], v[132:133], v[48:49] op_sel_hi:[0,1,1]
	v_fma_f32 v144, v48, v136, 0
	v_fmac_f32_e32 v144, v49, v137
	v_lshlrev_b32_e32 v134, 16, v65
	v_and_b32_e32 v135, 0xffff0000, v65
	v_pk_mul_f32 v[50:51], v[50:51], v[28:29] op_sel_hi:[1,0]
	v_lshlrev_b32_e32 v138, 16, v73
	v_and_b32_e32 v139, 0xffff0000, v73
	v_pk_fma_f32 v[50:51], v[30:31], v[134:135], v[50:51] op_sel_hi:[0,1,1]
	v_fmac_f32_e32 v144, v50, v138
	v_fmac_f32_e32 v144, v51, v139
	v_lshlrev_b32_e32 v132, 16, v66
	v_and_b32_e32 v133, 0xffff0000, v66
	v_pk_mul_f32 v[52:53], v[52:53], v[28:29] op_sel_hi:[1,0]
	v_lshlrev_b32_e32 v136, 16, v74
	v_and_b32_e32 v137, 0xffff0000, v74
	v_pk_fma_f32 v[52:53], v[30:31], v[132:133], v[52:53] op_sel_hi:[0,1,1]
	v_fmac_f32_e32 v144, v52, v136
	v_fmac_f32_e32 v144, v53, v137
	v_lshlrev_b32_e32 v134, 16, v67
	v_and_b32_e32 v135, 0xffff0000, v67
	v_pk_mul_f32 v[54:55], v[54:55], v[28:29] op_sel_hi:[1,0]
	v_lshlrev_b32_e32 v138, 16, v75
	v_and_b32_e32 v139, 0xffff0000, v75
	v_pk_fma_f32 v[54:55], v[30:31], v[134:135], v[54:55] op_sel_hi:[0,1,1]
	v_fmac_f32_e32 v144, v54, v138
	v_fmac_f32_e32 v144, v55, v139
	v_lshlrev_b32_e32 v132, 16, v68
	v_and_b32_e32 v133, 0xffff0000, v68
	v_pk_mul_f32 v[56:57], v[56:57], v[28:29] op_sel_hi:[1,0]
	v_lshlrev_b32_e32 v136, 16, v76
	v_and_b32_e32 v137, 0xffff0000, v76
	v_pk_fma_f32 v[56:57], v[30:31], v[132:133], v[56:57] op_sel_hi:[0,1,1]
	v_fmac_f32_e32 v144, v56, v136
	v_fmac_f32_e32 v144, v57, v137
	v_lshlrev_b32_e32 v134, 16, v69
	v_and_b32_e32 v135, 0xffff0000, v69
	v_pk_mul_f32 v[58:59], v[58:59], v[28:29] op_sel_hi:[1,0]
	v_lshlrev_b32_e32 v138, 16, v77
	v_and_b32_e32 v139, 0xffff0000, v77
	v_pk_fma_f32 v[58:59], v[30:31], v[134:135], v[58:59] op_sel_hi:[0,1,1]
	v_fmac_f32_e32 v144, v58, v138
	v_fmac_f32_e32 v144, v59, v139
	v_lshlrev_b32_e32 v132, 16, v70
	v_and_b32_e32 v133, 0xffff0000, v70
	v_pk_mul_f32 v[60:61], v[60:61], v[28:29] op_sel_hi:[1,0]
	v_lshlrev_b32_e32 v136, 16, v78
	v_and_b32_e32 v137, 0xffff0000, v78
	v_pk_fma_f32 v[60:61], v[30:31], v[132:133], v[60:61] op_sel_hi:[0,1,1]
	v_fmac_f32_e32 v144, v60, v136
	v_fmac_f32_e32 v144, v61, v137
	v_lshlrev_b32_e32 v134, 16, v71
	v_and_b32_e32 v135, 0xffff0000, v71
	v_pk_mul_f32 v[62:63], v[62:63], v[28:29] op_sel_hi:[1,0]
	v_lshlrev_b32_e32 v138, 16, v79
	v_and_b32_e32 v139, 0xffff0000, v79
	v_pk_fma_f32 v[62:63], v[30:31], v[134:135], v[62:63] op_sel_hi:[0,1,1]
	v_fmac_f32_e32 v144, v62, v138
	v_fmac_f32_e32 v144, v63, v139
	s_nop 1
	v_add_f32_dpp v144, v144, v144 quad_perm:[1,0,3,2] row_mask:0xf bank_mask:0xf
	s_nop 1
	v_add_f32_dpp v144, v144, v144 quad_perm:[2,3,0,1] row_mask:0xf bank_mask:0xf
	s_nop 1
	v_add_f32_dpp v144, v144, v144 row_shl:4 row_mask:0xf bank_mask:0xf
	s_nop 1
	v_fmac_f32_e32 v144, v25, v140
	v_cvt_pk_bf16_f32 v144, v144, v26
	s_waitcnt lgkmcnt(0)
	v_lshlrev_b32_e32 v141, 16, v129
	v_mul_f32_e32 v11, v21, v24
	v_mul_f32_e32 v11, 0xbfb8aa3b, v11
	v_exp_f32_e32 v28, v11
	v_mul_f32_e32 v30, v21, v141
	v_lshlrev_b32_e32 v132, 16, v80
	v_and_b32_e32 v133, 0xffff0000, v80
	v_pk_mul_f32 v[48:49], v[48:49], v[28:29] op_sel_hi:[1,0]
	v_lshlrev_b32_e32 v136, 16, v88
	v_and_b32_e32 v137, 0xffff0000, v88
	v_pk_fma_f32 v[48:49], v[30:31], v[132:133], v[48:49] op_sel_hi:[0,1,1]
	v_fma_f32 v145, v48, v136, 0
	v_fmac_f32_e32 v145, v49, v137
	v_lshlrev_b32_e32 v134, 16, v81
	v_and_b32_e32 v135, 0xffff0000, v81
	v_pk_mul_f32 v[50:51], v[50:51], v[28:29] op_sel_hi:[1,0]
	v_lshlrev_b32_e32 v138, 16, v89
	v_and_b32_e32 v139, 0xffff0000, v89
	v_pk_fma_f32 v[50:51], v[30:31], v[134:135], v[50:51] op_sel_hi:[0,1,1]
	v_fmac_f32_e32 v145, v50, v138
	v_fmac_f32_e32 v145, v51, v139
	v_lshlrev_b32_e32 v132, 16, v82
	v_and_b32_e32 v133, 0xffff0000, v82
	v_pk_mul_f32 v[52:53], v[52:53], v[28:29] op_sel_hi:[1,0]
	v_lshlrev_b32_e32 v136, 16, v90
	v_and_b32_e32 v137, 0xffff0000, v90
	v_pk_fma_f32 v[52:53], v[30:31], v[132:133], v[52:53] op_sel_hi:[0,1,1]
	v_fmac_f32_e32 v145, v52, v136
	v_fmac_f32_e32 v145, v53, v137
	v_lshlrev_b32_e32 v134, 16, v83
	v_and_b32_e32 v135, 0xffff0000, v83
	v_pk_mul_f32 v[54:55], v[54:55], v[28:29] op_sel_hi:[1,0]
	v_lshlrev_b32_e32 v138, 16, v91
	v_and_b32_e32 v139, 0xffff0000, v91
	v_pk_fma_f32 v[54:55], v[30:31], v[134:135], v[54:55] op_sel_hi:[0,1,1]
	v_fmac_f32_e32 v145, v54, v138
	v_fmac_f32_e32 v145, v55, v139
	v_lshlrev_b32_e32 v132, 16, v84
	v_and_b32_e32 v133, 0xffff0000, v84
	v_pk_mul_f32 v[56:57], v[56:57], v[28:29] op_sel_hi:[1,0]
	v_lshlrev_b32_e32 v136, 16, v92
	v_and_b32_e32 v137, 0xffff0000, v92
	v_pk_fma_f32 v[56:57], v[30:31], v[132:133], v[56:57] op_sel_hi:[0,1,1]
	v_fmac_f32_e32 v145, v56, v136
	v_fmac_f32_e32 v145, v57, v137
	v_lshlrev_b32_e32 v134, 16, v85
	v_and_b32_e32 v135, 0xffff0000, v85
	v_pk_mul_f32 v[58:59], v[58:59], v[28:29] op_sel_hi:[1,0]
	v_lshlrev_b32_e32 v138, 16, v93
	v_and_b32_e32 v139, 0xffff0000, v93
	v_pk_fma_f32 v[58:59], v[30:31], v[134:135], v[58:59] op_sel_hi:[0,1,1]
	v_fmac_f32_e32 v145, v58, v138
	v_fmac_f32_e32 v145, v59, v139
	v_lshlrev_b32_e32 v132, 16, v86
	v_and_b32_e32 v133, 0xffff0000, v86
	v_pk_mul_f32 v[60:61], v[60:61], v[28:29] op_sel_hi:[1,0]
	v_lshlrev_b32_e32 v136, 16, v94
	v_and_b32_e32 v137, 0xffff0000, v94
	v_pk_fma_f32 v[60:61], v[30:31], v[132:133], v[60:61] op_sel_hi:[0,1,1]
	v_fmac_f32_e32 v145, v60, v136
	v_fmac_f32_e32 v145, v61, v137
	v_lshlrev_b32_e32 v134, 16, v87
	v_and_b32_e32 v135, 0xffff0000, v87
	v_pk_mul_f32 v[62:63], v[62:63], v[28:29] op_sel_hi:[1,0]
	v_lshlrev_b32_e32 v138, 16, v95
	v_and_b32_e32 v139, 0xffff0000, v95
	v_pk_fma_f32 v[62:63], v[30:31], v[134:135], v[62:63] op_sel_hi:[0,1,1]
	v_fmac_f32_e32 v145, v62, v138
	v_fmac_f32_e32 v145, v63, v139
	s_nop 1
	v_add_f32_dpp v145, v145, v145 quad_perm:[1,0,3,2] row_mask:0xf bank_mask:0xf
	s_nop 1
	v_add_f32_dpp v145, v145, v145 quad_perm:[2,3,0,1] row_mask:0xf bank_mask:0xf
	s_nop 1
	v_add_f32_dpp v145, v145, v145 row_shl:4 row_mask:0xf bank_mask:0xf
	s_nop 1
	v_fmac_f32_e32 v145, v25, v141
	v_cvt_pk_bf16_f32 v145, v145, v26
	v_lshlrev_b32_e32 v142, 16, v130
	v_mul_f32_e32 v11, v22, v24
	v_mul_f32_e32 v11, 0xbfb8aa3b, v11
	v_exp_f32_e32 v28, v11
	v_mul_f32_e32 v30, v22, v142
	v_lshlrev_b32_e32 v132, 16, v96
	v_and_b32_e32 v133, 0xffff0000, v96
	v_pk_mul_f32 v[48:49], v[48:49], v[28:29] op_sel_hi:[1,0]
	v_lshlrev_b32_e32 v136, 16, v104
	v_and_b32_e32 v137, 0xffff0000, v104
	v_pk_fma_f32 v[48:49], v[30:31], v[132:133], v[48:49] op_sel_hi:[0,1,1]
	v_fma_f32 v146, v48, v136, 0
	v_fmac_f32_e32 v146, v49, v137
	v_lshlrev_b32_e32 v134, 16, v97
	v_and_b32_e32 v135, 0xffff0000, v97
	v_pk_mul_f32 v[50:51], v[50:51], v[28:29] op_sel_hi:[1,0]
	v_lshlrev_b32_e32 v138, 16, v105
	v_and_b32_e32 v139, 0xffff0000, v105
	v_pk_fma_f32 v[50:51], v[30:31], v[134:135], v[50:51] op_sel_hi:[0,1,1]
	v_fmac_f32_e32 v146, v50, v138
	v_fmac_f32_e32 v146, v51, v139
	v_lshlrev_b32_e32 v132, 16, v98
	v_and_b32_e32 v133, 0xffff0000, v98
	v_pk_mul_f32 v[52:53], v[52:53], v[28:29] op_sel_hi:[1,0]
	v_lshlrev_b32_e32 v136, 16, v106
	v_and_b32_e32 v137, 0xffff0000, v106
	v_pk_fma_f32 v[52:53], v[30:31], v[132:133], v[52:53] op_sel_hi:[0,1,1]
	v_fmac_f32_e32 v146, v52, v136
	v_fmac_f32_e32 v146, v53, v137
	v_lshlrev_b32_e32 v134, 16, v99
	v_and_b32_e32 v135, 0xffff0000, v99
	v_pk_mul_f32 v[54:55], v[54:55], v[28:29] op_sel_hi:[1,0]
	v_lshlrev_b32_e32 v138, 16, v107
	v_and_b32_e32 v139, 0xffff0000, v107
	v_pk_fma_f32 v[54:55], v[30:31], v[134:135], v[54:55] op_sel_hi:[0,1,1]
	v_fmac_f32_e32 v146, v54, v138
	v_fmac_f32_e32 v146, v55, v139
	v_lshlrev_b32_e32 v132, 16, v100
	v_and_b32_e32 v133, 0xffff0000, v100
	v_pk_mul_f32 v[56:57], v[56:57], v[28:29] op_sel_hi:[1,0]
	v_lshlrev_b32_e32 v136, 16, v108
	v_and_b32_e32 v137, 0xffff0000, v108
	v_pk_fma_f32 v[56:57], v[30:31], v[132:133], v[56:57] op_sel_hi:[0,1,1]
	v_fmac_f32_e32 v146, v56, v136
	v_fmac_f32_e32 v146, v57, v137
	v_lshlrev_b32_e32 v134, 16, v101
	v_and_b32_e32 v135, 0xffff0000, v101
	v_pk_mul_f32 v[58:59], v[58:59], v[28:29] op_sel_hi:[1,0]
	v_lshlrev_b32_e32 v138, 16, v109
	v_and_b32_e32 v139, 0xffff0000, v109
	v_pk_fma_f32 v[58:59], v[30:31], v[134:135], v[58:59] op_sel_hi:[0,1,1]
	v_fmac_f32_e32 v146, v58, v138
	v_fmac_f32_e32 v146, v59, v139
	v_lshlrev_b32_e32 v132, 16, v102
	v_and_b32_e32 v133, 0xffff0000, v102
	v_pk_mul_f32 v[60:61], v[60:61], v[28:29] op_sel_hi:[1,0]
	v_lshlrev_b32_e32 v136, 16, v110
	v_and_b32_e32 v137, 0xffff0000, v110
	v_pk_fma_f32 v[60:61], v[30:31], v[132:133], v[60:61] op_sel_hi:[0,1,1]
	v_fmac_f32_e32 v146, v60, v136
	v_fmac_f32_e32 v146, v61, v137
	v_lshlrev_b32_e32 v134, 16, v103
	v_and_b32_e32 v135, 0xffff0000, v103
	v_pk_mul_f32 v[62:63], v[62:63], v[28:29] op_sel_hi:[1,0]
	v_lshlrev_b32_e32 v138, 16, v111
	v_and_b32_e32 v139, 0xffff0000, v111
	v_pk_fma_f32 v[62:63], v[30:31], v[134:135], v[62:63] op_sel_hi:[0,1,1]
	v_fmac_f32_e32 v146, v62, v138
	v_fmac_f32_e32 v146, v63, v139
	s_nop 1
	v_add_f32_dpp v146, v146, v146 quad_perm:[1,0,3,2] row_mask:0xf bank_mask:0xf
	s_nop 1
	v_add_f32_dpp v146, v146, v146 quad_perm:[2,3,0,1] row_mask:0xf bank_mask:0xf
	s_nop 1
	v_add_f32_dpp v146, v146, v146 row_shl:4 row_mask:0xf bank_mask:0xf
	s_nop 1
	v_fmac_f32_e32 v146, v25, v142
	v_cvt_pk_bf16_f32 v146, v146, v26
	v_lshlrev_b32_e32 v143, 16, v131
	v_mul_f32_e32 v11, v23, v24
	v_mul_f32_e32 v11, 0xbfb8aa3b, v11
	v_exp_f32_e32 v28, v11
	v_mul_f32_e32 v30, v23, v143
	v_lshlrev_b32_e32 v132, 16, v112
	v_and_b32_e32 v133, 0xffff0000, v112
	v_pk_mul_f32 v[48:49], v[48:49], v[28:29] op_sel_hi:[1,0]
	v_lshlrev_b32_e32 v136, 16, v120
	v_and_b32_e32 v137, 0xffff0000, v120
	v_pk_fma_f32 v[48:49], v[30:31], v[132:133], v[48:49] op_sel_hi:[0,1,1]
	v_fma_f32 v147, v48, v136, 0
	v_fmac_f32_e32 v147, v49, v137
	v_lshlrev_b32_e32 v134, 16, v113
	v_and_b32_e32 v135, 0xffff0000, v113
	v_pk_mul_f32 v[50:51], v[50:51], v[28:29] op_sel_hi:[1,0]
	v_lshlrev_b32_e32 v138, 16, v121
	v_and_b32_e32 v139, 0xffff0000, v121
	v_pk_fma_f32 v[50:51], v[30:31], v[134:135], v[50:51] op_sel_hi:[0,1,1]
	v_fmac_f32_e32 v147, v50, v138
	v_fmac_f32_e32 v147, v51, v139
	v_lshlrev_b32_e32 v132, 16, v114
	v_and_b32_e32 v133, 0xffff0000, v114
	v_pk_mul_f32 v[52:53], v[52:53], v[28:29] op_sel_hi:[1,0]
	v_lshlrev_b32_e32 v136, 16, v122
	v_and_b32_e32 v137, 0xffff0000, v122
	v_pk_fma_f32 v[52:53], v[30:31], v[132:133], v[52:53] op_sel_hi:[0,1,1]
	v_fmac_f32_e32 v147, v52, v136
	v_fmac_f32_e32 v147, v53, v137
	v_lshlrev_b32_e32 v134, 16, v115
	v_and_b32_e32 v135, 0xffff0000, v115
	v_pk_mul_f32 v[54:55], v[54:55], v[28:29] op_sel_hi:[1,0]
	v_lshlrev_b32_e32 v138, 16, v123
	v_and_b32_e32 v139, 0xffff0000, v123
	v_pk_fma_f32 v[54:55], v[30:31], v[134:135], v[54:55] op_sel_hi:[0,1,1]
	v_fmac_f32_e32 v147, v54, v138
	v_fmac_f32_e32 v147, v55, v139
	v_lshlrev_b32_e32 v132, 16, v116
	v_and_b32_e32 v133, 0xffff0000, v116
	v_pk_mul_f32 v[56:57], v[56:57], v[28:29] op_sel_hi:[1,0]
	v_lshlrev_b32_e32 v136, 16, v124
	v_and_b32_e32 v137, 0xffff0000, v124
	v_pk_fma_f32 v[56:57], v[30:31], v[132:133], v[56:57] op_sel_hi:[0,1,1]
	v_fmac_f32_e32 v147, v56, v136
	v_fmac_f32_e32 v147, v57, v137
	v_lshlrev_b32_e32 v134, 16, v117
	v_and_b32_e32 v135, 0xffff0000, v117
	v_pk_mul_f32 v[58:59], v[58:59], v[28:29] op_sel_hi:[1,0]
	v_lshlrev_b32_e32 v138, 16, v125
	v_and_b32_e32 v139, 0xffff0000, v125
	v_pk_fma_f32 v[58:59], v[30:31], v[134:135], v[58:59] op_sel_hi:[0,1,1]
	v_fmac_f32_e32 v147, v58, v138
	v_fmac_f32_e32 v147, v59, v139
	v_lshlrev_b32_e32 v132, 16, v118
	v_and_b32_e32 v133, 0xffff0000, v118
	v_pk_mul_f32 v[60:61], v[60:61], v[28:29] op_sel_hi:[1,0]
	v_lshlrev_b32_e32 v136, 16, v126
	v_and_b32_e32 v137, 0xffff0000, v126
	v_pk_fma_f32 v[60:61], v[30:31], v[132:133], v[60:61] op_sel_hi:[0,1,1]
	v_fmac_f32_e32 v147, v60, v136
	v_fmac_f32_e32 v147, v61, v137
	v_lshlrev_b32_e32 v134, 16, v119
	v_and_b32_e32 v135, 0xffff0000, v119
	v_pk_mul_f32 v[62:63], v[62:63], v[28:29] op_sel_hi:[1,0]
	v_lshlrev_b32_e32 v138, 16, v127
	v_and_b32_e32 v139, 0xffff0000, v127
	v_pk_fma_f32 v[62:63], v[30:31], v[134:135], v[62:63] op_sel_hi:[0,1,1]
	v_fmac_f32_e32 v147, v62, v138
	v_fmac_f32_e32 v147, v63, v139
	s_nop 1
	v_add_f32_dpp v147, v147, v147 quad_perm:[1,0,3,2] row_mask:0xf bank_mask:0xf
	s_nop 1
	v_add_f32_dpp v147, v147, v147 quad_perm:[2,3,0,1] row_mask:0xf bank_mask:0xf
	s_nop 1
	v_add_f32_dpp v147, v147, v147 row_shl:4 row_mask:0xf bank_mask:0xf
	s_nop 1
	v_fmac_f32_e32 v147, v25, v143
	v_cvt_pk_bf16_f32 v147, v147, v26
	s_mov_b64 s[0:1], exec
	s_and_b64 exec, exec, s[38:39]
	global_store_short v4, v144, s[30:31]
	global_store_short v4, v145, s[30:31] offset:2048
	global_store_short v5, v146, s[30:31]
	global_store_short v5, v147, s[30:31] offset:2048
	s_mov_b64 exec, s[0:1]
	global_store_dwordx4 v1, v[48:51], s[28:29] nt
	global_store_dwordx4 v1, v[52:55], s[28:29] offset:16 nt
	global_store_dwordx4 v1, v[56:59], s[28:29] offset:32 nt
	global_store_dwordx4 v1, v[60:63], s[28:29] offset:48 nt
	s_cmp_eq_u32 s33, 0
	s_cbranch_scc1 .Lss_exit
	s_waitcnt vmcnt(12)
	s_mov_b64 s[0:1], exec
	s_and_b64 exec, exec, s[46:47]
	s_cbranch_execz .Lss_nowr_b
	ds_write_b128 v7, v[16:19]
.Lss_nowr_b:
	s_mov_b64 exec, s[0:1]
	s_mov_b32 s22, s24
	s_branch .Lss_loop
.Lss_exit:
	s_barrier
.Lss_ret:
	s_cmp_eq_u32 s48, 0
	s_cbranch_scc0 .LBB0_248

.LBB0_217:
	v_readlane_b32 s0, v255, 14
	v_readlane_b32 s68, v255, 10
	v_readlane_b32 s1, v255, 15
	v_readlane_b32 s69, v255, 11
	v_readlane_b32 s58, v254, 20
	v_readlane_b32 s60, v254, 22
	v_readlane_b32 s62, v254, 24
	v_readlane_b32 s64, v254, 26
	v_readlane_b32 s66, v254, 28
	v_readlane_b32 s72, v254, 30
	v_readlane_b32 s74, v254, 32
	v_readlane_b32 s76, v254, 34
	v_readlane_b32 s78, v254, 36
	v_readlane_b32 s86, v254, 38
	v_readlane_b32 s88, v254, 40
	v_readlane_b32 s90, v254, 42
	v_readlane_b32 s92, v254, 44
	v_readlane_b32 s94, v254, 46
	v_readlane_b32 s96, v254, 48
	v_readlane_b32 s50, v254, 50
	v_readlane_b32 s52, v254, 52
	v_readlane_b32 s80, v254, 54
	s_andn2_b64 vcc, exec, s[0:1]
	v_readlane_b32 s54, v254, 19
	v_readlane_b32 s70, v255, 12
	v_readlane_b32 s71, v255, 13
	v_readlane_b32 s59, v254, 21
	v_readlane_b32 s61, v254, 23
	v_readlane_b32 s63, v254, 25
	v_readlane_b32 s65, v254, 27
	v_readlane_b32 s67, v254, 29
	v_readlane_b32 s73, v254, 31
	v_readlane_b32 s75, v254, 33
	v_readlane_b32 s77, v254, 35
	v_readlane_b32 s79, v254, 37
	v_readlane_b32 s87, v254, 39
	v_readlane_b32 s89, v254, 41
	v_readlane_b32 s91, v254, 43
	v_readlane_b32 s93, v254, 45
	v_readlane_b32 s95, v254, 47
	v_readlane_b32 s97, v254, 49
	v_readlane_b32 s51, v254, 51
	v_readlane_b32 s53, v254, 53
	v_readlane_b32 s81, v254, 55
	s_movk_i32 s55, 0x4200
	s_movk_i32 s49, 0x41ff
	s_movk_i32 s68, 0x7f0
	s_movk_i32 s69, 0x5000
	s_mov_b32 s82, 0xb000
	s_mov_b32 s83, 0xd000
	s_movk_i32 s84, 0x5800
	s_movk_i32 s85, 0x7fd
	s_mov_b64 s[56:57], 0xb000
	s_cbranch_vccnz .LBB0_248
	s_mov_b32 s48, 1
	s_branch .Lss_entry

.LBB0_256:
	s_mov_b32 s0, 0x66666667
	v_mul_hi_i32 v2, v1, s0
	s_mov_b32 s0, 0x50000
	v_lshrrev_b32_e32 v3, 31, v2
	v_ashrrev_i32_e32 v2, 7, v2
	v_cmp_gt_i32_e64 s[6:7], s0, v1
	s_mov_b32 s0, 0x4ffff
	v_add_u32_e32 v2, v2, v3
	v_cmp_lt_i32_e64 s[4:5], s0, v1
	s_and_saveexec_b64 s[0:1], s[4:5]
	s_xor_b64 s[0:1], exec, s[0:1]
	v_add_u32_e32 v136, 0xfffffc00, v2
	v_lshl_add_u32 v178, v136, 2, v229
	s_or_saveexec_b64 s[0:1], s[0:1]
	v_mov_b32_e32 v27, 0
	s_xor_b64 exec, exec, s[0:1]
	v_lshlrev_b32_e32 v178, 4, v2
	v_ashrrev_i32_e32 v136, 7, v2
	v_and_b32_e32 v27, 0x7f0, v178
	s_or_b64 exec, exec, s[0:1]
	v_mul_i32_i24_e32 v2, 0x140, v2
	v_sub_u32_e32 v2, v1, v2
	s_movk_i32 s0, 0xbf
	v_cmp_lt_i32_e32 vcc, s0, v2
	v_lshlrev_b32_e32 v180, 3, v2
	s_mov_b64 s[0:1], 0
	s_and_saveexec_b64 s[24:25], vcc
	s_xor_b64 s[24:25], exec, s[24:25]
	s_cbranch_execz .LBB0_283
	v_readlane_b32 s0, v254, 56
	v_readlane_b32 s1, v254, 57
	s_load_dwordx2 s[0:1], s[0:1], 0x28
	v_mul_lo_u32 v136, v136, 15
	v_ashrrev_i32_e32 v137, 31, v136
	v_add_u32_e32 v132, 0xfffffa00, v180
	v_lshlrev_b64 v[138:139], 12, v[136:137]
	v_lshrrev_b32_e32 v151, 8, v132
	v_mov_b32_e32 v133, v26
	s_waitcnt lgkmcnt(0)
	v_lshl_add_u64 v[2:3], s[0:1], 0, v[138:139]
	v_lshlrev_b32_e64 v150, v151, 2
	v_lshl_add_u64 v[140:141], v[132:133], 2, v[2:3]
	s_and_saveexec_b64 s[0:1], s[4:5]
	s_xor_b64 s[0:1], exec, s[0:1]
	s_cbranch_execz .LBB0_265
	s_waitcnt vmcnt(0)
	v_lshlrev_b64 v[2:3], 10, v[136:137]
	s_mov_b64 s[30:31], 0x4000
	v_lshl_add_u64 v[4:5], v[140:141], 0, s[30:31]
	s_mov_b64 s[30:31], 0x1000
	v_readlane_b32 s34, v254, 56
	v_readlane_b32 s35, v254, 57
	s_load_dwordx2 s[34:35], s[34:35], 0x100
	global_load_dwordx4 v[28:31], v[4:5], off
	global_load_dwordx4 v[32:35], v[4:5], off offset:16
	v_lshl_add_u64 v[4:5], v[4:5], 0, s[30:31]
	global_load_dwordx4 v[36:39], v[4:5], off
	global_load_dwordx4 v[40:43], v[4:5], off offset:16
	v_lshl_add_u64 v[4:5], v[4:5], 0, s[30:31]
	global_load_dwordx4 v[44:47], v[4:5], off
	global_load_dwordx4 v[48:51], v[4:5], off offset:16
	v_lshl_add_u64 v[4:5], v[4:5], 0, s[30:31]
	global_load_dwordx4 v[52:55], v[4:5], off
	global_load_dwordx4 v[56:59], v[4:5], off offset:16
	v_lshl_add_u64 v[4:5], v[4:5], 0, s[30:31]
	global_load_dwordx4 v[60:63], v[4:5], off
	global_load_dwordx4 v[64:67], v[4:5], off offset:16
	v_lshl_add_u64 v[4:5], v[4:5], 0, s[30:31]
	global_load_dwordx4 v[68:71], v[4:5], off
	global_load_dwordx4 v[72:75], v[4:5], off offset:16
	v_lshl_add_u64 v[4:5], v[4:5], 0, s[30:31]
	global_load_dwordx4 v[76:79], v[4:5], off
	global_load_dwordx4 v[80:83], v[4:5], off offset:16
	v_lshl_add_u64 v[4:5], v[4:5], 0, s[30:31]
	global_load_dwordx4 v[84:87], v[4:5], off
	global_load_dwordx4 v[88:91], v[4:5], off offset:16
	v_lshl_add_u64 v[4:5], v[4:5], 0, s[30:31]
	global_load_dwordx4 v[92:95], v[4:5], off
	global_load_dwordx4 v[96:99], v[4:5], off offset:16
	v_lshl_add_u64 v[4:5], v[4:5], 0, s[30:31]
	global_load_dwordx4 v[100:103], v[4:5], off
	global_load_dwordx4 v[104:107], v[4:5], off offset:16
	v_lshl_add_u64 v[4:5], v[4:5], 0, s[30:31]
	global_load_dwordx4 v[108:111], v[4:5], off
	global_load_dwordx4 v[112:115], v[4:5], off offset:16
	v_mov_b32_e32 v12, 0
	v_mov_b32_e32 v13, v12
	v_mov_b32_e32 v124, v12
	v_mov_b32_e32 v125, v12
	v_mov_b32_e32 v16, v12
	v_mov_b32_e32 v17, v12
	v_mov_b32_e32 v14, v12
	v_mov_b32_e32 v15, v12
	s_waitcnt lgkmcnt(0)
	v_lshl_add_u64 v[2:3], v[2:3], 2, s[34:35]
	v_lshl_add_u64 v[2:3], v[132:133], 2, v[2:3]
	s_mov_b64 s[34:35], 0x88dc000
	v_lshl_add_u64 v[6:7], v[2:3], 0, s[34:35]
	s_waitcnt vmcnt(20)
	global_store_dwordx4 v[6:7], v[28:31], off
	global_store_dwordx4 v[6:7], v[32:35], off offset:16
	v_lshl_add_u64 v[6:7], v[6:7], 0, s[30:31]
	s_waitcnt vmcnt(20)
	global_store_dwordx4 v[6:7], v[36:39], off
	global_store_dwordx4 v[6:7], v[40:43], off offset:16
	v_lshl_add_u64 v[6:7], v[6:7], 0, s[30:31]
	s_waitcnt vmcnt(20)
	global_store_dwordx4 v[6:7], v[44:47], off
	global_store_dwordx4 v[6:7], v[48:51], off offset:16
	v_lshl_add_u64 v[6:7], v[6:7], 0, s[30:31]
	s_waitcnt vmcnt(20)
	global_store_dwordx4 v[6:7], v[52:55], off
	global_store_dwordx4 v[6:7], v[56:59], off offset:16
	v_lshl_add_u64 v[6:7], v[6:7], 0, s[30:31]
	s_waitcnt vmcnt(20)
	global_store_dwordx4 v[6:7], v[60:63], off
	global_store_dwordx4 v[6:7], v[64:67], off offset:16
	v_lshl_add_u64 v[6:7], v[6:7], 0, s[30:31]
	s_waitcnt vmcnt(20)
	global_store_dwordx4 v[6:7], v[68:71], off
	global_store_dwordx4 v[6:7], v[72:75], off offset:16
	v_lshl_add_u64 v[6:7], v[6:7], 0, s[30:31]
	s_waitcnt vmcnt(20)
	global_store_dwordx4 v[6:7], v[76:79], off
	global_store_dwordx4 v[6:7], v[80:83], off offset:16
	v_lshl_add_u64 v[6:7], v[6:7], 0, s[30:31]
	s_waitcnt vmcnt(20)
	global_store_dwordx4 v[6:7], v[84:87], off
	global_store_dwordx4 v[6:7], v[88:91], off offset:16
	v_lshl_add_u64 v[6:7], v[6:7], 0, s[30:31]
	s_waitcnt vmcnt(20)
	global_store_dwordx4 v[6:7], v[92:95], off
	global_store_dwordx4 v[6:7], v[96:99], off offset:16
	v_lshl_add_u64 v[6:7], v[6:7], 0, s[30:31]
	s_waitcnt vmcnt(20)
	global_store_dwordx4 v[6:7], v[100:103], off
	global_store_dwordx4 v[6:7], v[104:107], off offset:16
	v_lshl_add_u64 v[6:7], v[6:7], 0, s[30:31]
	s_waitcnt vmcnt(20)
	global_store_dwordx4 v[6:7], v[108:111], off
	global_store_dwordx4 v[6:7], v[112:115], off offset:16
	v_pk_add_f32 v[12:13], v[12:13], v[108:109]
	v_pk_add_f32 v[124:125], v[124:125], v[110:111]
	v_pk_add_f32 v[16:17], v[16:17], v[112:113]
	v_pk_add_f32 v[14:15], v[14:15], v[114:115]
	v_cmp_le_u32_e64 s[26:27], 4, v150
	s_and_saveexec_b64 s[28:29], s[26:27]
	v_pk_add_f32 v[12:13], v[12:13], v[100:101]
	v_pk_add_f32 v[124:125], v[124:125], v[102:103]
	v_pk_add_f32 v[16:17], v[16:17], v[104:105]
	v_pk_add_f32 v[14:15], v[14:15], v[106:107]
	v_pk_add_f32 v[12:13], v[12:13], v[92:93]
	v_pk_add_f32 v[124:125], v[124:125], v[94:95]
	v_pk_add_f32 v[16:17], v[16:17], v[96:97]
	v_pk_add_f32 v[14:15], v[14:15], v[98:99]
	v_cmp_le_u32_e64 s[26:27], 8, v150
	s_and_b64 exec, exec, s[26:27]
	v_pk_add_f32 v[12:13], v[12:13], v[84:85]
	v_pk_add_f32 v[124:125], v[124:125], v[86:87]
	v_pk_add_f32 v[16:17], v[16:17], v[88:89]
	v_pk_add_f32 v[14:15], v[14:15], v[90:91]
	v_pk_add_f32 v[12:13], v[12:13], v[76:77]
	v_pk_add_f32 v[124:125], v[124:125], v[78:79]
	v_pk_add_f32 v[16:17], v[16:17], v[80:81]
	v_pk_add_f32 v[14:15], v[14:15], v[82:83]
	v_pk_add_f32 v[12:13], v[12:13], v[68:69]
	v_pk_add_f32 v[124:125], v[124:125], v[70:71]
	v_pk_add_f32 v[16:17], v[16:17], v[72:73]
	v_pk_add_f32 v[14:15], v[14:15], v[74:75]
	v_pk_add_f32 v[12:13], v[12:13], v[60:61]
	v_pk_add_f32 v[124:125], v[124:125], v[62:63]
	v_pk_add_f32 v[16:17], v[16:17], v[64:65]
	v_pk_add_f32 v[14:15], v[14:15], v[66:67]
	v_cmp_le_u32_e64 s[26:27], 16, v150
	s_and_b64 exec, exec, s[26:27]
	s_cbranch_execz .Lpool_hist_done
	v_pk_add_f32 v[12:13], v[12:13], v[52:53]
	v_pk_add_f32 v[124:125], v[124:125], v[54:55]
	v_pk_add_f32 v[16:17], v[16:17], v[56:57]
	v_pk_add_f32 v[14:15], v[14:15], v[58:59]
	v_pk_add_f32 v[12:13], v[12:13], v[44:45]
	v_pk_add_f32 v[124:125], v[124:125], v[46:47]
	v_pk_add_f32 v[16:17], v[16:17], v[48:49]
	v_pk_add_f32 v[14:15], v[14:15], v[50:51]
	v_pk_add_f32 v[12:13], v[12:13], v[36:37]
	v_pk_add_f32 v[124:125], v[124:125], v[38:39]
	v_pk_add_f32 v[16:17], v[16:17], v[40:41]
	v_pk_add_f32 v[14:15], v[14:15], v[42:43]
	v_pk_add_f32 v[12:13], v[12:13], v[28:29]
	v_pk_add_f32 v[124:125], v[124:125], v[30:31]
	v_pk_add_f32 v[16:17], v[16:17], v[32:33]
	v_pk_add_f32 v[14:15], v[14:15], v[34:35]
	s_mov_b64 s[34:35], 0x3000
	v_lshl_add_u64 v[4:5], v[140:141], 0, s[34:35]
	global_load_dwordx4 v[28:31], v[4:5], off
	global_load_dwordx4 v[32:35], v[4:5], off offset:16
	s_mov_b64 s[34:35], 0x2000
	v_lshl_add_u64 v[4:5], v[140:141], 0, s[34:35]
	global_load_dwordx4 v[36:39], v[4:5], off
	global_load_dwordx4 v[40:43], v[4:5], off offset:16
	s_mov_b64 s[34:35], 0x1000
	v_lshl_add_u64 v[4:5], v[140:141], 0, s[34:35]
	global_load_dwordx4 v[44:47], v[4:5], off
	global_load_dwordx4 v[48:51], v[4:5], off offset:16
	global_load_dwordx4 v[52:55], v[140:141], off
	global_load_dwordx4 v[56:59], v[140:141], off offset:16
	s_waitcnt vmcnt(6)
	v_pk_add_f32 v[12:13], v[12:13], v[28:29]
	v_pk_add_f32 v[124:125], v[124:125], v[30:31]
	v_pk_add_f32 v[16:17], v[16:17], v[32:33]
	v_pk_add_f32 v[14:15], v[14:15], v[34:35]
	s_waitcnt vmcnt(4)
	v_pk_add_f32 v[12:13], v[12:13], v[36:37]
	v_pk_add_f32 v[124:125], v[124:125], v[38:39]
	v_pk_add_f32 v[16:17], v[16:17], v[40:41]
	v_pk_add_f32 v[14:15], v[14:15], v[42:43]
	s_waitcnt vmcnt(2)
	v_pk_add_f32 v[12:13], v[12:13], v[44:45]
	v_pk_add_f32 v[124:125], v[124:125], v[46:47]
	v_pk_add_f32 v[16:17], v[16:17], v[48:49]
	v_pk_add_f32 v[14:15], v[14:15], v[50:51]
	s_waitcnt vmcnt(0)
	v_pk_add_f32 v[12:13], v[12:13], v[52:53]
	v_pk_add_f32 v[124:125], v[124:125], v[54:55]
	v_pk_add_f32 v[16:17], v[16:17], v[56:57]
	v_pk_add_f32 v[14:15], v[14:15], v[58:59]
.Lpool_hist_done:
	s_mov_b64 exec, s[28:29]

.LBB0_531:
	v_add_u32_e32 v32, s23, v1
	s_ashr_i32 s23, s22, 31
	s_lshl_b64 s[22:23], s[22:23], 2
	s_waitcnt lgkmcnt(0)
	s_add_u32 s2, s2, s22
	s_addc_u32 s3, s3, s23
	v_mov_b32_e32 v39, v26
	v_ashrrev_i32_e32 v33, 31, v32
	v_lshl_add_u64 v[34:35], s[2:3], 0, v[38:39]
	v_mul_lo_u32 v30, s4, v33
	v_mul_lo_u32 v31, s5, v32
	v_mad_u64_u32 v[28:29], s[2:3], s4, v32, 0
	v_add3_u32 v29, v29, v30, v31
	v_lshl_add_u64 v[28:29], v[28:29], 2, v[34:35]
	global_load_dwordx4 v[28:31], v[28:29], off nt
	s_cmp_lg_u64 s[0:1], 0
	s_cselect_b64 s[2:3], -1, 0
	s_cmp_eq_u64 s[0:1], 0
	v_lshl_add_u64 v[40:41], v[32:33], 2, s[0:1]
	v_mov_b32_e32 v232, 1.0
	s_cbranch_scc1 .LBB0_533
	global_load_dword v232, v[40:41], off
.LBB0_533:
	v_add_u32_e32 v32, 32, v32
	v_ashrrev_i32_e32 v33, 31, v32
	v_mul_lo_u32 v39, s4, v33
	v_mul_lo_u32 v42, s5, v32
	v_mad_u64_u32 v[32:33], s[0:1], s4, v32, 0
	v_add3_u32 v33, v33, v39, v42
	v_lshl_add_u64 v[32:33], v[32:33], 2, v[34:35]
	global_load_dwordx4 v[32:35], v[32:33], off nt
	s_andn2_b64 vcc, exec, s[2:3]
	v_mov_b32_e32 v234, 1.0
	s_cbranch_vccnz .LBB0_535
	global_load_dword v234, v[40:41], off offset:128

.LBB0_557:
	v_add_u32_e32 v18, s25, v1
	s_ashr_i32 s25, s24, 31
	s_lshl_b64 s[24:25], s[24:25], 2
	s_waitcnt lgkmcnt(0)
	s_add_u32 s2, s2, s24
	s_addc_u32 s3, s3, s25
	v_mov_b32_e32 v39, v26
	v_ashrrev_i32_e32 v19, 31, v18
	v_lshl_add_u64 v[20:21], s[2:3], 0, v[38:39]
	v_mul_lo_u32 v8, s4, v19
	v_mul_lo_u32 v9, s5, v18
	v_mad_u64_u32 v[6:7], s[2:3], s4, v18, 0
	v_add3_u32 v7, v7, v8, v9
	v_lshl_add_u64 v[6:7], v[6:7], 2, v[20:21]
	global_load_dwordx4 v[6:9], v[6:7], off nt
	s_cmp_lg_u64 s[0:1], 0
	s_cselect_b64 s[2:3], -1, 0
	s_cmp_eq_u64 s[0:1], 0
	v_lshl_add_u64 v[40:41], v[18:19], 2, s[0:1]
	v_mov_b32_e32 v236, 1.0
	s_cbranch_scc1 .LBB0_559
	global_load_dword v236, v[40:41], off
.LBB0_559:
	v_add_u32_e32 v18, 32, v18
	v_ashrrev_i32_e32 v19, 31, v18
	v_mul_lo_u32 v39, s4, v19
	v_mul_lo_u32 v42, s5, v18
	v_mad_u64_u32 v[18:19], s[0:1], s4, v18, 0
	v_add3_u32 v19, v19, v39, v42
	v_lshl_add_u64 v[18:19], v[18:19], 2, v[20:21]
	global_load_dwordx4 v[18:21], v[18:19], off nt
	s_andn2_b64 vcc, exec, s[2:3]
	v_mov_b32_e32 v238, 1.0
	s_cbranch_vccnz .LBB0_561
	global_load_dword v238, v[40:41], off offset:128

.LBB0_583:
	v_add_u32_e32 v22, s27, v1
	s_ashr_i32 s27, s26, 31
	s_lshl_b64 s[26:27], s[26:27], 2
	s_waitcnt lgkmcnt(0)
	s_add_u32 s2, s2, s26
	s_addc_u32 s3, s3, s27
	v_mov_b32_e32 v39, v26
	v_ashrrev_i32_e32 v23, 31, v22
	v_lshl_add_u64 v[24:25], s[2:3], 0, v[38:39]
	v_mul_lo_u32 v12, s4, v23
	v_mul_lo_u32 v13, s5, v22
	v_mad_u64_u32 v[10:11], s[2:3], s4, v22, 0
	v_add3_u32 v11, v11, v12, v13
	v_lshl_add_u64 v[10:11], v[10:11], 2, v[24:25]
	global_load_dwordx4 v[10:13], v[10:11], off nt
	s_cmp_lg_u64 s[0:1], 0
	s_cselect_b64 s[2:3], -1, 0
	s_cmp_eq_u64 s[0:1], 0
	v_lshl_add_u64 v[40:41], v[22:23], 2, s[0:1]
	v_mov_b32_e32 v240, 1.0
	s_cbranch_scc1 .LBB0_585
	global_load_dword v240, v[40:41], off
.LBB0_585:
	v_add_u32_e32 v22, 32, v22
	v_ashrrev_i32_e32 v23, 31, v22
	v_mul_lo_u32 v39, s4, v23
	v_mul_lo_u32 v42, s5, v22
	v_mad_u64_u32 v[22:23], s[0:1], s4, v22, 0
	v_add3_u32 v23, v23, v39, v42
	v_lshl_add_u64 v[22:23], v[22:23], 2, v[24:25]
	global_load_dwordx4 v[22:25], v[22:23], off nt
	s_andn2_b64 vcc, exec, s[2:3]
	v_mov_b32_e32 v242, 1.0
	s_cbranch_vccnz .LBB0_587
	global_load_dword v242, v[40:41], off offset:128

.LBB0_609:
	v_add_u32_e32 v14, s29, v1
	s_ashr_i32 s29, s28, 31
	s_lshl_b64 s[28:29], s[28:29], 2
	s_waitcnt lgkmcnt(0)
	s_add_u32 s2, s2, s28
	s_addc_u32 s3, s3, s29
	v_mov_b32_e32 v39, v26
	v_ashrrev_i32_e32 v15, 31, v14
	v_lshl_add_u64 v[16:17], s[2:3], 0, v[38:39]
	v_mul_lo_u32 v4, s4, v15
	v_mul_lo_u32 v5, s5, v14
	v_mad_u64_u32 v[2:3], s[2:3], s4, v14, 0
	v_add3_u32 v3, v3, v4, v5
	v_lshl_add_u64 v[2:3], v[2:3], 2, v[16:17]
	global_load_dwordx4 v[2:5], v[2:3], off nt
	s_cmp_lg_u64 s[0:1], 0
	s_cselect_b64 s[2:3], -1, 0
	s_cmp_eq_u64 s[0:1], 0
	v_lshl_add_u64 v[40:41], v[14:15], 2, s[0:1]
	v_mov_b32_e32 v244, 1.0
	s_cbranch_scc1 .LBB0_611
	global_load_dword v244, v[40:41], off
.LBB0_611:
	v_add_u32_e32 v14, 32, v14
	v_ashrrev_i32_e32 v15, 31, v14
	v_mul_lo_u32 v39, s4, v15
	v_mul_lo_u32 v42, s5, v14
	v_mad_u64_u32 v[14:15], s[0:1], s4, v14, 0
	v_add3_u32 v15, v15, v39, v42
	v_lshl_add_u64 v[14:15], v[14:15], 2, v[16:17]
	global_load_dwordx4 v[14:17], v[14:15], off nt
	s_andn2_b64 vcc, exec, s[2:3]
	v_mov_b32_e32 v246, 1.0
	s_cbranch_vccnz .LBB0_613
	global_load_dword v246, v[40:41], off offset:128
.LBB0_613:
	s_waitcnt vmcnt(0)
	v_pk_mul_f32 v[28:29], v[28:29], v[232:233] op_sel_hi:[1,0]
	v_pk_mul_f32 v[30:31], v[30:31], v[232:233] op_sel_hi:[1,0]
	v_pk_mul_f32 v[32:33], v[32:33], v[234:235] op_sel_hi:[1,0]
	v_pk_mul_f32 v[34:35], v[34:35], v[234:235] op_sel_hi:[1,0]
	v_pk_mul_f32 v[6:7], v[6:7], v[236:237] op_sel_hi:[1,0]
	v_pk_mul_f32 v[8:9], v[8:9], v[236:237] op_sel_hi:[1,0]
	v_pk_mul_f32 v[18:19], v[18:19], v[238:239] op_sel_hi:[1,0]
	v_pk_mul_f32 v[20:21], v[20:21], v[238:239] op_sel_hi:[1,0]
	v_pk_mul_f32 v[10:11], v[10:11], v[240:241] op_sel_hi:[1,0]
	v_pk_mul_f32 v[12:13], v[12:13], v[240:241] op_sel_hi:[1,0]
	v_pk_mul_f32 v[22:23], v[22:23], v[242:243] op_sel_hi:[1,0]
	v_pk_mul_f32 v[24:25], v[24:25], v[242:243] op_sel_hi:[1,0]
	v_pk_mul_f32 v[2:3], v[2:3], v[244:245] op_sel_hi:[1,0]
	v_pk_mul_f32 v[4:5], v[4:5], v[244:245] op_sel_hi:[1,0]
	v_pk_mul_f32 v[14:15], v[14:15], v[246:247] op_sel_hi:[1,0]
	v_pk_mul_f32 v[16:17], v[16:17], v[246:247] op_sel_hi:[1,0]
	ds_write2_b32 v49, v28, v29 offset1:1
	ds_write2_b32 v49, v30, v31 offset0:2 offset1:3
	v_add_u32_e32 v28, 0x2080, v49
	v_cndmask_b32_e64 v29, 0, 1, s[22:23]
	s_waitcnt vmcnt(0)
	ds_write2_b32 v28, v32, v33 offset1:1
	v_add_u32_e32 v28, 0x2088, v49
	v_cmp_ne_u32_e64 s[4:5], 1, v29
	s_andn2_b64 vcc, exec, s[22:23]
	ds_write2_b32 v28, v34, v35 offset1:1
	s_cbranch_vccnz .LBB0_631
	v_add_u32_e32 v28, 0x4100, v49
	ds_write2_b32 v28, v6, v7 offset1:1
	v_add_u32_e32 v28, 0x4108, v49
	ds_write2_b32 v28, v8, v9 offset1:1
	v_add_u32_e32 v28, 0x6180, v49
	ds_write2_b32 v28, v18, v19 offset1:1
	v_add_u32_e32 v28, 0x6188, v49
	ds_write2_b32 v28, v20, v21 offset1:1
	v_cndmask_b32_e64 v28, 0, 1, s[24:25]
	v_cmp_ne_u32_e64 s[2:3], 1, v28
	s_andn2_b64 vcc, exec, s[24:25]
	s_cbranch_vccz .LBB0_632
